# GEMM accumulator zero-init: 252 v_mov_b32 pairs -> v_pk_mov_b32 (PA, out-proj, mlp1, mlp2 tile prologues); on top of previous
# baseline (speedup 1.0000x reference)
.Lsw_done:
	s_ashr_i32 s21, s20, 31
	s_lshl_b64 s[14:15], s[20:21], 19
	s_add_u32 s14, s90, s14
	s_addc_u32 s15, s91, s15
	s_and_b64 s[16:17], s[44:45], exec
	s_cselect_b32 s21, s15, s23
	s_cselect_b32 s28, s14, s22
	s_ashr_i32 s19, s18, 31
	s_lshl_b64 s[16:17], s[18:19], 19
	s_add_u32 s16, s5, s16
	s_addc_u32 s17, s89, s17
	s_and_b64 s[26:27], s[44:45], exec
	s_cselect_b32 s19, s17, s25
	s_cselect_b32 s29, s16, s24
	s_add_u32 s22, s22, 0x40080
	s_addc_u32 s23, s23, 0
	s_add_u32 s30, s24, 0x100
	v_mov_b32_e32 v0, 0
	s_addc_u32 s31, s25, 0
	s_mov_b32 s34, -2
	v_mov_b32_e32 v1, v0
	v_pk_mov_b32 v[2:3], v[0:1], v[0:1] op_sel:[0,1]
	v_pk_mov_b32 v[4:5], v[0:1], v[0:1] op_sel:[0,1]
	v_pk_mov_b32 v[6:7], v[0:1], v[0:1] op_sel:[0,1]
	v_pk_mov_b32 v[16:17], v[0:1], v[0:1] op_sel:[0,1]
	v_pk_mov_b32 v[18:19], v[0:1], v[0:1] op_sel:[0,1]
	v_pk_mov_b32 v[20:21], v[0:1], v[0:1] op_sel:[0,1]
	v_pk_mov_b32 v[22:23], v[0:1], v[0:1] op_sel:[0,1]
	v_pk_mov_b32 v[32:33], v[0:1], v[0:1] op_sel:[0,1]
	v_pk_mov_b32 v[34:35], v[0:1], v[0:1] op_sel:[0,1]
	v_pk_mov_b32 v[36:37], v[0:1], v[0:1] op_sel:[0,1]
	v_pk_mov_b32 v[38:39], v[0:1], v[0:1] op_sel:[0,1]
	v_pk_mov_b32 v[48:49], v[0:1], v[0:1] op_sel:[0,1]
	v_pk_mov_b32 v[50:51], v[0:1], v[0:1] op_sel:[0,1]
	v_pk_mov_b32 v[52:53], v[0:1], v[0:1] op_sel:[0,1]
	v_pk_mov_b32 v[54:55], v[0:1], v[0:1] op_sel:[0,1]
	v_pk_mov_b32 v[8:9], v[0:1], v[0:1] op_sel:[0,1]
	v_pk_mov_b32 v[10:11], v[0:1], v[0:1] op_sel:[0,1]
	v_pk_mov_b32 v[12:13], v[0:1], v[0:1] op_sel:[0,1]
	v_pk_mov_b32 v[14:15], v[0:1], v[0:1] op_sel:[0,1]
	v_pk_mov_b32 v[24:25], v[0:1], v[0:1] op_sel:[0,1]
	v_pk_mov_b32 v[26:27], v[0:1], v[0:1] op_sel:[0,1]
	v_pk_mov_b32 v[28:29], v[0:1], v[0:1] op_sel:[0,1]
	v_pk_mov_b32 v[30:31], v[0:1], v[0:1] op_sel:[0,1]
	v_pk_mov_b32 v[40:41], v[0:1], v[0:1] op_sel:[0,1]
	v_pk_mov_b32 v[42:43], v[0:1], v[0:1] op_sel:[0,1]
	v_pk_mov_b32 v[44:45], v[0:1], v[0:1] op_sel:[0,1]
	v_pk_mov_b32 v[46:47], v[0:1], v[0:1] op_sel:[0,1]
	v_pk_mov_b32 v[56:57], v[0:1], v[0:1] op_sel:[0,1]
	v_pk_mov_b32 v[58:59], v[0:1], v[0:1] op_sel:[0,1]
	v_pk_mov_b32 v[60:61], v[0:1], v[0:1] op_sel:[0,1]
	v_pk_mov_b32 v[62:63], v[0:1], v[0:1] op_sel:[0,1]
	v_pk_mov_b32 v[64:65], v[0:1], v[0:1] op_sel:[0,1]
	v_pk_mov_b32 v[66:67], v[0:1], v[0:1] op_sel:[0,1]
	v_pk_mov_b32 v[68:69], v[0:1], v[0:1] op_sel:[0,1]
	v_pk_mov_b32 v[70:71], v[0:1], v[0:1] op_sel:[0,1]
	v_pk_mov_b32 v[80:81], v[0:1], v[0:1] op_sel:[0,1]
	v_pk_mov_b32 v[82:83], v[0:1], v[0:1] op_sel:[0,1]
	v_pk_mov_b32 v[84:85], v[0:1], v[0:1] op_sel:[0,1]
	v_pk_mov_b32 v[86:87], v[0:1], v[0:1] op_sel:[0,1]
	v_pk_mov_b32 v[96:97], v[0:1], v[0:1] op_sel:[0,1]
	v_pk_mov_b32 v[98:99], v[0:1], v[0:1] op_sel:[0,1]
	v_pk_mov_b32 v[100:101], v[0:1], v[0:1] op_sel:[0,1]
	v_pk_mov_b32 v[102:103], v[0:1], v[0:1] op_sel:[0,1]
	v_pk_mov_b32 v[112:113], v[0:1], v[0:1] op_sel:[0,1]
	v_pk_mov_b32 v[114:115], v[0:1], v[0:1] op_sel:[0,1]
	v_pk_mov_b32 v[116:117], v[0:1], v[0:1] op_sel:[0,1]
	v_pk_mov_b32 v[118:119], v[0:1], v[0:1] op_sel:[0,1]
	v_pk_mov_b32 v[72:73], v[0:1], v[0:1] op_sel:[0,1]
	v_pk_mov_b32 v[74:75], v[0:1], v[0:1] op_sel:[0,1]
	v_pk_mov_b32 v[76:77], v[0:1], v[0:1] op_sel:[0,1]
	v_pk_mov_b32 v[78:79], v[0:1], v[0:1] op_sel:[0,1]
	v_pk_mov_b32 v[88:89], v[0:1], v[0:1] op_sel:[0,1]
	v_pk_mov_b32 v[90:91], v[0:1], v[0:1] op_sel:[0,1]
	v_pk_mov_b32 v[92:93], v[0:1], v[0:1] op_sel:[0,1]
	v_pk_mov_b32 v[94:95], v[0:1], v[0:1] op_sel:[0,1]
	v_pk_mov_b32 v[104:105], v[0:1], v[0:1] op_sel:[0,1]
	v_pk_mov_b32 v[106:107], v[0:1], v[0:1] op_sel:[0,1]
	v_pk_mov_b32 v[108:109], v[0:1], v[0:1] op_sel:[0,1]
	v_pk_mov_b32 v[110:111], v[0:1], v[0:1] op_sel:[0,1]
	v_pk_mov_b32 v[120:121], v[0:1], v[0:1] op_sel:[0,1]
	v_pk_mov_b32 v[122:123], v[0:1], v[0:1] op_sel:[0,1]
	v_pk_mov_b32 v[124:125], v[0:1], v[0:1] op_sel:[0,1]
	v_pk_mov_b32 v[126:127], v[0:1], v[0:1] op_sel:[0,1]

.LBB0_1501:
	s_add_i32 s75, s36, 2
	s_add_u32 s34, s30, 0x100
	s_addc_u32 s35, s31, 0
	s_add_i32 s76, 0, 0x10000
	s_cmp_eq_u32 s1, s36
	s_cselect_b32 s41, s25, s35
	s_cselect_b32 s40, s71, s34
	s_cselect_b32 s37, s23, s74
	s_cselect_b32 s36, s72, s73
	s_add_i32 s77, 0, 0x14000
	v_add_u32_e32 v152, s76, v138
	v_add_u32_e32 v168, s77, v138
	ds_read_b128 v[140:143], v152
	ds_read_b128 v[144:147], v152 offset:1024
	ds_read_b128 v[148:151], v152 offset:2048
	ds_read_b128 v[152:155], v152 offset:3072
	ds_read_b128 v[156:159], v168
	ds_read_b128 v[160:163], v168 offset:1024
	ds_read_b128 v[164:167], v168 offset:2048
	ds_read_b128 v[168:171], v168 offset:3072
	v_lshl_add_u64 v[204:205], s[30:31], 0, v[132:133]
	s_add_i32 m0, s58, 0xc000
	ds_read_b128 v[172:175], v139
	ds_read_b128 v[176:179], v139 offset:1024
	ds_read_b128 v[180:183], v139 offset:2048
	ds_read_b128 v[184:187], v139 offset:3072
	ds_read_b128 v[188:191], v139 offset:4096
	ds_read_b128 v[192:195], v139 offset:5120
	ds_read_b128 v[196:199], v139 offset:6144
	ds_read_b128 v[200:203], v139 offset:7168
	global_load_lds_dwordx4 v[204:205], off
	v_lshl_add_u64 v[204:205], s[30:31], 0, v[134:135]
	s_add_i32 m0, s58, 0xe000
	s_nop 0
	global_load_lds_dwordx4 v[204:205], off
	s_waitcnt vmcnt(8)
	s_waitcnt lgkmcnt(0)
	s_barrier
	s_setprio 1
	s_waitcnt lgkmcnt(0)
	v_mfma_f32_16x16x32_bf16 v[124:127], v[140:143], v[172:175], v[124:127]
	v_mfma_f32_16x16x32_bf16 v[108:111], v[148:151], v[172:175], v[108:111]
	v_mfma_f32_16x16x32_bf16 v[120:123], v[140:143], v[180:183], v[120:123]
	v_mfma_f32_16x16x32_bf16 v[104:107], v[148:151], v[180:183], v[104:107]
	v_mfma_f32_16x16x32_bf16 v[116:119], v[140:143], v[188:191], v[116:119]
	v_mfma_f32_16x16x32_bf16 v[100:103], v[148:151], v[188:191], v[100:103]
	v_mfma_f32_16x16x32_bf16 v[112:115], v[140:143], v[196:199], v[112:115]
	v_mfma_f32_16x16x32_bf16 v[96:99], v[148:151], v[196:199], v[96:99]
	v_mfma_f32_16x16x32_bf16 v[124:127], v[144:147], v[176:179], v[124:127]
	v_mfma_f32_16x16x32_bf16 v[108:111], v[152:155], v[176:179], v[108:111]
	v_mfma_f32_16x16x32_bf16 v[120:123], v[144:147], v[184:187], v[120:123]
	v_mfma_f32_16x16x32_bf16 v[104:107], v[152:155], v[184:187], v[104:107]
	v_mfma_f32_16x16x32_bf16 v[116:119], v[144:147], v[192:195], v[116:119]
	v_mfma_f32_16x16x32_bf16 v[100:103], v[152:155], v[192:195], v[100:103]
	v_mfma_f32_16x16x32_bf16 v[112:115], v[144:147], v[200:203], v[112:115]
	v_mfma_f32_16x16x32_bf16 v[96:99], v[152:155], v[200:203], v[96:99]
	s_setprio 0
	s_setprio 1
	v_mfma_f32_16x16x32_bf16 v[92:95], v[156:159], v[172:175], v[92:95]
	v_mfma_f32_16x16x32_bf16 v[76:79], v[164:167], v[172:175], v[76:79]
	v_mfma_f32_16x16x32_bf16 v[88:91], v[156:159], v[180:183], v[88:91]
	v_mfma_f32_16x16x32_bf16 v[72:75], v[164:167], v[180:183], v[72:75]
	v_mfma_f32_16x16x32_bf16 v[84:87], v[156:159], v[188:191], v[84:87]
	v_mfma_f32_16x16x32_bf16 v[68:71], v[164:167], v[188:191], v[68:71]
	v_mfma_f32_16x16x32_bf16 v[80:83], v[156:159], v[196:199], v[80:83]
	v_mfma_f32_16x16x32_bf16 v[64:67], v[164:167], v[196:199], v[64:67]
	v_mfma_f32_16x16x32_bf16 v[92:95], v[160:163], v[176:179], v[92:95]
	v_mfma_f32_16x16x32_bf16 v[76:79], v[168:171], v[176:179], v[76:79]
	v_mfma_f32_16x16x32_bf16 v[88:91], v[160:163], v[184:187], v[88:91]
	v_mfma_f32_16x16x32_bf16 v[72:75], v[168:171], v[184:187], v[72:75]
	v_mfma_f32_16x16x32_bf16 v[84:87], v[160:163], v[192:195], v[84:87]
	v_mfma_f32_16x16x32_bf16 v[68:71], v[168:171], v[192:195], v[68:71]
	v_mfma_f32_16x16x32_bf16 v[80:83], v[160:163], v[200:203], v[80:83]
	v_mfma_f32_16x16x32_bf16 v[64:67], v[168:171], v[200:203], v[64:67]
	s_setprio 0
	s_barrier
	s_add_i32 s30, s76, s56
	v_lshl_add_u64 v[204:205], s[36:37], 0, v[128:129]
	s_mov_b32 m0, s30
	ds_read_b128 v[172:175], v139 offset:16384
	ds_read_b128 v[176:179], v139 offset:17408
	ds_read_b128 v[180:183], v139 offset:18432
	ds_read_b128 v[184:187], v139 offset:19456
	ds_read_b128 v[188:191], v139 offset:20480
	ds_read_b128 v[192:195], v139 offset:21504
	ds_read_b128 v[196:199], v139 offset:22528
	ds_read_b128 v[200:203], v139 offset:23552
	global_load_lds_dwordx4 v[204:205], off
	s_add_i32 m0, s30, 0x2000
	s_add_u32 s30, s36, 0x40000
	v_lshl_add_u64 v[206:207], s[36:37], 0, v[130:131]
	s_addc_u32 s31, s37, 0
	s_add_i32 s76, s77, s56
	global_load_lds_dwordx4 v[206:207], off
	v_lshl_add_u64 v[208:209], s[30:31], 0, v[128:129]
	s_mov_b32 m0, s76
	v_lshl_add_u64 v[210:211], s[40:41], 0, v[130:131]
	global_load_lds_dwordx4 v[208:209], off
	v_lshl_add_u64 v[208:209], s[30:31], 0, v[130:131]
	s_add_i32 m0, s76, 0x2000
	s_nop 0
	global_load_lds_dwordx4 v[208:209], off
	v_lshl_add_u64 v[208:209], s[40:41], 0, v[128:129]
	s_mov_b32 m0, s58
	s_nop 0
	global_load_lds_dwordx4 v[208:209], off
	s_mov_b32 m0, s60
	s_nop 0
	global_load_lds_dwordx4 v[210:211], off
	s_waitcnt vmcnt(8)
	s_waitcnt lgkmcnt(0)
	s_barrier
	s_setprio 1
	s_waitcnt lgkmcnt(0)
	v_mfma_f32_16x16x32_bf16 v[60:63], v[140:143], v[172:175], v[60:63]
	v_mfma_f32_16x16x32_bf16 v[44:47], v[148:151], v[172:175], v[44:47]
	v_mfma_f32_16x16x32_bf16 v[56:59], v[140:143], v[180:183], v[56:59]
	v_mfma_f32_16x16x32_bf16 v[40:43], v[148:151], v[180:183], v[40:43]
	v_mfma_f32_16x16x32_bf16 v[52:55], v[140:143], v[188:191], v[52:55]
	v_mfma_f32_16x16x32_bf16 v[36:39], v[148:151], v[188:191], v[36:39]
	v_mfma_f32_16x16x32_bf16 v[48:51], v[140:143], v[196:199], v[48:51]
	v_mfma_f32_16x16x32_bf16 v[32:35], v[148:151], v[196:199], v[32:35]
	v_mfma_f32_16x16x32_bf16 v[60:63], v[144:147], v[176:179], v[60:63]
	v_mfma_f32_16x16x32_bf16 v[44:47], v[152:155], v[176:179], v[44:47]
	v_mfma_f32_16x16x32_bf16 v[56:59], v[144:147], v[184:187], v[56:59]
	v_mfma_f32_16x16x32_bf16 v[40:43], v[152:155], v[184:187], v[40:43]
	v_mfma_f32_16x16x32_bf16 v[52:55], v[144:147], v[192:195], v[52:55]
	v_mfma_f32_16x16x32_bf16 v[36:39], v[152:155], v[192:195], v[36:39]
	v_mfma_f32_16x16x32_bf16 v[48:51], v[144:147], v[200:203], v[48:51]
	v_mfma_f32_16x16x32_bf16 v[32:35], v[152:155], v[200:203], v[32:35]
	s_setprio 0
	s_setprio 1
	v_mfma_f32_16x16x32_bf16 v[28:31], v[156:159], v[172:175], v[28:31]
	v_mfma_f32_16x16x32_bf16 v[12:15], v[164:167], v[172:175], v[12:15]
	v_mfma_f32_16x16x32_bf16 v[24:27], v[156:159], v[180:183], v[24:27]
	v_mfma_f32_16x16x32_bf16 v[8:11], v[164:167], v[180:183], v[8:11]
	v_mfma_f32_16x16x32_bf16 v[20:23], v[156:159], v[188:191], v[20:23]
	v_mfma_f32_16x16x32_bf16 v[4:7], v[164:167], v[188:191], v[4:7]
	v_mfma_f32_16x16x32_bf16 v[16:19], v[156:159], v[196:199], v[16:19]
	v_mfma_f32_16x16x32_bf16 v[0:3], v[164:167], v[196:199], v[0:3]
	v_mfma_f32_16x16x32_bf16 v[28:31], v[160:163], v[176:179], v[28:31]
	v_mfma_f32_16x16x32_bf16 v[12:15], v[168:171], v[176:179], v[12:15]
	v_mfma_f32_16x16x32_bf16 v[24:27], v[160:163], v[184:187], v[24:27]
	v_mfma_f32_16x16x32_bf16 v[8:11], v[168:171], v[184:187], v[8:11]
	v_mfma_f32_16x16x32_bf16 v[20:23], v[160:163], v[192:195], v[20:23]
	v_mfma_f32_16x16x32_bf16 v[4:7], v[168:171], v[192:195], v[4:7]
	v_mfma_f32_16x16x32_bf16 v[16:19], v[160:163], v[200:203], v[16:19]
	v_mfma_f32_16x16x32_bf16 v[0:3], v[168:171], v[200:203], v[0:3]
	s_setprio 0
	s_barrier
	s_add_i32 s76, 0, 0x18000
	s_add_i32 s77, 0, 0x1c000
	v_add_u32_e32 v152, s76, v138
	v_add_u32_e32 v168, s77, v138
	ds_read_b128 v[140:143], v152
	ds_read_b128 v[144:147], v152 offset:1024
	ds_read_b128 v[148:151], v152 offset:2048
	ds_read_b128 v[152:155], v152 offset:3072
	ds_read_b128 v[156:159], v168
	ds_read_b128 v[160:163], v168 offset:1024
	ds_read_b128 v[164:167], v168 offset:2048
	ds_read_b128 v[168:171], v168 offset:3072
	s_add_u32 s30, s40, 0x40000
	s_addc_u32 s31, s41, 0
	s_mov_b32 m0, s61
	v_lshl_add_u64 v[212:213], s[30:31], 0, v[128:129]
	ds_read_b128 v[172:175], v139 offset:32768
	ds_read_b128 v[176:179], v139 offset:33792
	ds_read_b128 v[180:183], v139 offset:34816
	ds_read_b128 v[184:187], v139 offset:35840
	ds_read_b128 v[188:191], v139 offset:36864
	ds_read_b128 v[192:195], v139 offset:37888
	ds_read_b128 v[196:199], v139 offset:38912
	ds_read_b128 v[200:203], v139 offset:39936
	global_load_lds_dwordx4 v[212:213], off
	v_lshl_add_u64 v[212:213], s[30:31], 0, v[130:131]
	s_mov_b32 m0, s62
	s_nop 0
	global_load_lds_dwordx4 v[212:213], off
	s_waitcnt vmcnt(8)
	s_waitcnt lgkmcnt(0)
	s_barrier
	s_setprio 1
	s_waitcnt lgkmcnt(0)
	v_mfma_f32_16x16x32_bf16 v[124:127], v[140:143], v[172:175], v[124:127]
	v_mfma_f32_16x16x32_bf16 v[108:111], v[148:151], v[172:175], v[108:111]
	v_mfma_f32_16x16x32_bf16 v[120:123], v[140:143], v[180:183], v[120:123]
	v_mfma_f32_16x16x32_bf16 v[104:107], v[148:151], v[180:183], v[104:107]
	v_mfma_f32_16x16x32_bf16 v[116:119], v[140:143], v[188:191], v[116:119]
	v_mfma_f32_16x16x32_bf16 v[100:103], v[148:151], v[188:191], v[100:103]
	v_mfma_f32_16x16x32_bf16 v[112:115], v[140:143], v[196:199], v[112:115]
	v_mfma_f32_16x16x32_bf16 v[96:99], v[148:151], v[196:199], v[96:99]
	v_mfma_f32_16x16x32_bf16 v[124:127], v[144:147], v[176:179], v[124:127]
	v_mfma_f32_16x16x32_bf16 v[108:111], v[152:155], v[176:179], v[108:111]
	v_mfma_f32_16x16x32_bf16 v[120:123], v[144:147], v[184:187], v[120:123]
	v_mfma_f32_16x16x32_bf16 v[104:107], v[152:155], v[184:187], v[104:107]
	v_mfma_f32_16x16x32_bf16 v[116:119], v[144:147], v[192:195], v[116:119]
	v_mfma_f32_16x16x32_bf16 v[100:103], v[152:155], v[192:195], v[100:103]
	v_mfma_f32_16x16x32_bf16 v[112:115], v[144:147], v[200:203], v[112:115]
	v_mfma_f32_16x16x32_bf16 v[96:99], v[152:155], v[200:203], v[96:99]
	s_setprio 0
	s_setprio 1
	v_mfma_f32_16x16x32_bf16 v[92:95], v[156:159], v[172:175], v[92:95]
	v_mfma_f32_16x16x32_bf16 v[76:79], v[164:167], v[172:175], v[76:79]
	v_mfma_f32_16x16x32_bf16 v[88:91], v[156:159], v[180:183], v[88:91]
	v_mfma_f32_16x16x32_bf16 v[72:75], v[164:167], v[180:183], v[72:75]
	v_mfma_f32_16x16x32_bf16 v[84:87], v[156:159], v[188:191], v[84:87]
	v_mfma_f32_16x16x32_bf16 v[68:71], v[164:167], v[188:191], v[68:71]
	v_mfma_f32_16x16x32_bf16 v[80:83], v[156:159], v[196:199], v[80:83]
	v_mfma_f32_16x16x32_bf16 v[64:67], v[164:167], v[196:199], v[64:67]
	v_mfma_f32_16x16x32_bf16 v[92:95], v[160:163], v[176:179], v[92:95]
	v_mfma_f32_16x16x32_bf16 v[76:79], v[168:171], v[176:179], v[76:79]
	v_mfma_f32_16x16x32_bf16 v[88:91], v[160:163], v[184:187], v[88:91]
	v_mfma_f32_16x16x32_bf16 v[72:75], v[168:171], v[184:187], v[72:75]
	v_mfma_f32_16x16x32_bf16 v[84:87], v[160:163], v[192:195], v[84:87]
	v_mfma_f32_16x16x32_bf16 v[68:71], v[168:171], v[192:195], v[68:71]
	v_mfma_f32_16x16x32_bf16 v[80:83], v[160:163], v[200:203], v[80:83]
	v_mfma_f32_16x16x32_bf16 v[64:67], v[168:171], v[200:203], v[64:67]
	s_setprio 0
	s_barrier
	s_add_i32 s30, s76, s56
	v_lshl_add_u64 v[204:205], v[204:205], 0, s[6:7]
	s_mov_b32 m0, s30
	ds_read_b128 v[172:175], v139 offset:49152
	ds_read_b128 v[176:179], v139 offset:50176
	ds_read_b128 v[180:183], v139 offset:51200
	ds_read_b128 v[184:187], v139 offset:52224
	ds_read_b128 v[188:191], v139 offset:53248
	ds_read_b128 v[192:195], v139 offset:54272
	ds_read_b128 v[196:199], v139 offset:55296
	ds_read_b128 v[200:203], v139 offset:56320
	global_load_lds_dwordx4 v[204:205], off
	s_add_i32 m0, s30, 0x2000
	s_add_u32 s30, s36, 0x40080
	v_lshl_add_u64 v[204:205], v[206:207], 0, s[6:7]
	s_addc_u32 s31, s37, 0
	s_add_i32 s36, s77, s56
	global_load_lds_dwordx4 v[204:205], off
	v_lshl_add_u64 v[204:205], s[30:31], 0, v[128:129]
	s_mov_b32 m0, s36
	s_nop 0
	global_load_lds_dwordx4 v[204:205], off
	v_lshl_add_u64 v[204:205], s[30:31], 0, v[130:131]
	s_add_i32 m0, s36, 0x2000
	s_nop 0
	global_load_lds_dwordx4 v[204:205], off
	v_lshl_add_u64 v[204:205], v[208:209], 0, s[6:7]
	s_mov_b32 m0, s63
	s_nop 0
	global_load_lds_dwordx4 v[204:205], off
	v_lshl_add_u64 v[204:205], v[210:211], 0, s[6:7]
	s_mov_b32 m0, s64
	s_nop 0
	global_load_lds_dwordx4 v[204:205], off
	s_waitcnt vmcnt(8)
	s_waitcnt lgkmcnt(0)
	s_barrier
	s_setprio 1
	s_waitcnt lgkmcnt(0)
	v_mfma_f32_16x16x32_bf16 v[60:63], v[140:143], v[172:175], v[60:63]
	v_mfma_f32_16x16x32_bf16 v[44:47], v[148:151], v[172:175], v[44:47]
	v_mfma_f32_16x16x32_bf16 v[56:59], v[140:143], v[180:183], v[56:59]
	v_mfma_f32_16x16x32_bf16 v[40:43], v[148:151], v[180:183], v[40:43]
	v_mfma_f32_16x16x32_bf16 v[52:55], v[140:143], v[188:191], v[52:55]
	v_mfma_f32_16x16x32_bf16 v[36:39], v[148:151], v[188:191], v[36:39]
	v_mfma_f32_16x16x32_bf16 v[48:51], v[140:143], v[196:199], v[48:51]
	v_mfma_f32_16x16x32_bf16 v[32:35], v[148:151], v[196:199], v[32:35]
	v_mfma_f32_16x16x32_bf16 v[60:63], v[144:147], v[176:179], v[60:63]
	v_mfma_f32_16x16x32_bf16 v[44:47], v[152:155], v[176:179], v[44:47]
	v_mfma_f32_16x16x32_bf16 v[56:59], v[144:147], v[184:187], v[56:59]
	v_mfma_f32_16x16x32_bf16 v[40:43], v[152:155], v[184:187], v[40:43]
	v_mfma_f32_16x16x32_bf16 v[52:55], v[144:147], v[192:195], v[52:55]
	v_mfma_f32_16x16x32_bf16 v[36:39], v[152:155], v[192:195], v[36:39]
	v_mfma_f32_16x16x32_bf16 v[48:51], v[144:147], v[200:203], v[48:51]
	v_mfma_f32_16x16x32_bf16 v[32:35], v[152:155], v[200:203], v[32:35]
	s_setprio 0
	s_setprio 1
	v_mfma_f32_16x16x32_bf16 v[28:31], v[156:159], v[172:175], v[28:31]
	v_mfma_f32_16x16x32_bf16 v[12:15], v[164:167], v[172:175], v[12:15]
	v_mfma_f32_16x16x32_bf16 v[24:27], v[156:159], v[180:183], v[24:27]
	v_mfma_f32_16x16x32_bf16 v[8:11], v[164:167], v[180:183], v[8:11]
	v_mfma_f32_16x16x32_bf16 v[20:23], v[156:159], v[188:191], v[20:23]
	v_mfma_f32_16x16x32_bf16 v[4:7], v[164:167], v[188:191], v[4:7]
	v_mfma_f32_16x16x32_bf16 v[16:19], v[156:159], v[196:199], v[16:19]
	v_mfma_f32_16x16x32_bf16 v[0:3], v[164:167], v[196:199], v[0:3]
	v_mfma_f32_16x16x32_bf16 v[28:31], v[160:163], v[176:179], v[28:31]
	v_mfma_f32_16x16x32_bf16 v[12:15], v[168:171], v[176:179], v[12:15]
	v_mfma_f32_16x16x32_bf16 v[24:27], v[160:163], v[184:187], v[24:27]
	v_mfma_f32_16x16x32_bf16 v[8:11], v[168:171], v[184:187], v[8:11]
	v_mfma_f32_16x16x32_bf16 v[20:23], v[160:163], v[192:195], v[20:23]
	v_mfma_f32_16x16x32_bf16 v[4:7], v[168:171], v[192:195], v[4:7]
	v_mfma_f32_16x16x32_bf16 v[16:19], v[160:163], v[200:203], v[16:19]
	v_mfma_f32_16x16x32_bf16 v[0:3], v[168:171], v[200:203], v[0:3]
	s_setprio 0
	s_barrier
	s_add_u32 s73, s73, 0x100
	s_addc_u32 s74, s74, 0
	s_cmp_ge_u32 s75, s92
	s_mov_b64 s[30:31], s[34:35]
	s_mov_b32 s36, s75
	s_cbranch_scc0 .LBB0_1501
	s_andn2_b64 vcc, exec, s[50:51]
	s_cbranch_vccnz .LBB0_1493
	v_mov_b32_e32 v0, 0
	s_mov_b32 s66, s22
	s_mov_b32 s65, s24
	s_mov_b64 s[18:19], s[28:29]
	s_mov_b64 s[20:21], s[26:27]
	s_mov_b32 s68, s70
	v_mov_b32_e32 v1, v0
	v_pk_mov_b32 v[2:3], v[0:1], v[0:1] op_sel:[0,1]
	v_pk_mov_b32 v[16:17], v[0:1], v[0:1] op_sel:[0,1]
	v_pk_mov_b32 v[18:19], v[0:1], v[0:1] op_sel:[0,1]
	v_pk_mov_b32 v[4:5], v[0:1], v[0:1] op_sel:[0,1]
	v_pk_mov_b32 v[6:7], v[0:1], v[0:1] op_sel:[0,1]
	v_pk_mov_b32 v[20:21], v[0:1], v[0:1] op_sel:[0,1]
	v_pk_mov_b32 v[22:23], v[0:1], v[0:1] op_sel:[0,1]
	v_pk_mov_b32 v[8:9], v[0:1], v[0:1] op_sel:[0,1]
	v_pk_mov_b32 v[10:11], v[0:1], v[0:1] op_sel:[0,1]
	v_pk_mov_b32 v[24:25], v[0:1], v[0:1] op_sel:[0,1]
	v_pk_mov_b32 v[26:27], v[0:1], v[0:1] op_sel:[0,1]
	v_pk_mov_b32 v[12:13], v[0:1], v[0:1] op_sel:[0,1]
	v_pk_mov_b32 v[14:15], v[0:1], v[0:1] op_sel:[0,1]
	v_pk_mov_b32 v[28:29], v[0:1], v[0:1] op_sel:[0,1]
	v_pk_mov_b32 v[30:31], v[0:1], v[0:1] op_sel:[0,1]
	v_pk_mov_b32 v[32:33], v[0:1], v[0:1] op_sel:[0,1]
	v_pk_mov_b32 v[34:35], v[0:1], v[0:1] op_sel:[0,1]
	v_pk_mov_b32 v[48:49], v[0:1], v[0:1] op_sel:[0,1]
	v_pk_mov_b32 v[50:51], v[0:1], v[0:1] op_sel:[0,1]
	v_pk_mov_b32 v[36:37], v[0:1], v[0:1] op_sel:[0,1]
	v_pk_mov_b32 v[38:39], v[0:1], v[0:1] op_sel:[0,1]
	v_pk_mov_b32 v[52:53], v[0:1], v[0:1] op_sel:[0,1]
	v_pk_mov_b32 v[54:55], v[0:1], v[0:1] op_sel:[0,1]
	v_pk_mov_b32 v[40:41], v[0:1], v[0:1] op_sel:[0,1]
	v_pk_mov_b32 v[42:43], v[0:1], v[0:1] op_sel:[0,1]
	v_pk_mov_b32 v[56:57], v[0:1], v[0:1] op_sel:[0,1]
	v_pk_mov_b32 v[58:59], v[0:1], v[0:1] op_sel:[0,1]
	v_pk_mov_b32 v[44:45], v[0:1], v[0:1] op_sel:[0,1]
	v_pk_mov_b32 v[46:47], v[0:1], v[0:1] op_sel:[0,1]
	v_pk_mov_b32 v[60:61], v[0:1], v[0:1] op_sel:[0,1]
	v_pk_mov_b32 v[62:63], v[0:1], v[0:1] op_sel:[0,1]
	v_pk_mov_b32 v[64:65], v[0:1], v[0:1] op_sel:[0,1]
	v_pk_mov_b32 v[66:67], v[0:1], v[0:1] op_sel:[0,1]
	v_pk_mov_b32 v[80:81], v[0:1], v[0:1] op_sel:[0,1]
	v_pk_mov_b32 v[82:83], v[0:1], v[0:1] op_sel:[0,1]
	v_pk_mov_b32 v[68:69], v[0:1], v[0:1] op_sel:[0,1]
	v_pk_mov_b32 v[70:71], v[0:1], v[0:1] op_sel:[0,1]
	v_pk_mov_b32 v[84:85], v[0:1], v[0:1] op_sel:[0,1]
	v_pk_mov_b32 v[86:87], v[0:1], v[0:1] op_sel:[0,1]
	v_pk_mov_b32 v[72:73], v[0:1], v[0:1] op_sel:[0,1]
	v_pk_mov_b32 v[74:75], v[0:1], v[0:1] op_sel:[0,1]
	v_pk_mov_b32 v[88:89], v[0:1], v[0:1] op_sel:[0,1]
	v_pk_mov_b32 v[90:91], v[0:1], v[0:1] op_sel:[0,1]
	v_pk_mov_b32 v[76:77], v[0:1], v[0:1] op_sel:[0,1]
	v_pk_mov_b32 v[78:79], v[0:1], v[0:1] op_sel:[0,1]
	v_pk_mov_b32 v[92:93], v[0:1], v[0:1] op_sel:[0,1]
	v_pk_mov_b32 v[94:95], v[0:1], v[0:1] op_sel:[0,1]
	v_pk_mov_b32 v[96:97], v[0:1], v[0:1] op_sel:[0,1]
	v_pk_mov_b32 v[98:99], v[0:1], v[0:1] op_sel:[0,1]
	v_pk_mov_b32 v[112:113], v[0:1], v[0:1] op_sel:[0,1]
	v_pk_mov_b32 v[114:115], v[0:1], v[0:1] op_sel:[0,1]
	v_pk_mov_b32 v[100:101], v[0:1], v[0:1] op_sel:[0,1]
	v_pk_mov_b32 v[102:103], v[0:1], v[0:1] op_sel:[0,1]
	v_pk_mov_b32 v[116:117], v[0:1], v[0:1] op_sel:[0,1]
	v_pk_mov_b32 v[118:119], v[0:1], v[0:1] op_sel:[0,1]
	v_pk_mov_b32 v[104:105], v[0:1], v[0:1] op_sel:[0,1]
	v_pk_mov_b32 v[106:107], v[0:1], v[0:1] op_sel:[0,1]
	v_pk_mov_b32 v[120:121], v[0:1], v[0:1] op_sel:[0,1]
	v_pk_mov_b32 v[122:123], v[0:1], v[0:1] op_sel:[0,1]
	v_pk_mov_b32 v[108:109], v[0:1], v[0:1] op_sel:[0,1]
	v_pk_mov_b32 v[110:111], v[0:1], v[0:1] op_sel:[0,1]
	v_pk_mov_b32 v[124:125], v[0:1], v[0:1] op_sel:[0,1]
	v_pk_mov_b32 v[126:127], v[0:1], v[0:1] op_sel:[0,1]
	s_branch .LBB0_1493

.LBB0_1765:
	s_ashr_i32 s25, s24, 31
	s_lshl_b64 s[26:27], s[24:25], 19
	s_add_u32 s26, s5, s26
	s_addc_u32 s27, s38, s27
	s_and_b64 s[28:29], s[48:49], exec
	s_cselect_b32 s25, s27, s31
	s_cselect_b32 s62, s26, s30
	s_ashr_i32 s23, s22, 31
	s_lshl_b64 s[28:29], s[22:23], 19
	s_add_u32 s28, s39, s28
	s_addc_u32 s29, s40, s29
	s_and_b64 s[36:37], s[48:49], exec
	s_cselect_b32 s23, s29, s35
	s_cselect_b32 s63, s28, s34
	s_add_u32 s30, s30, 0x40080
	s_addc_u32 s31, s31, 0
	s_add_u32 s64, s34, 0x100
	v_mov_b32_e32 v0, 0
	s_addc_u32 s65, s35, 0
	s_mov_b32 s66, -2
	v_mov_b32_e32 v1, v0
	v_pk_mov_b32 v[2:3], v[0:1], v[0:1] op_sel:[0,1]
	v_pk_mov_b32 v[4:5], v[0:1], v[0:1] op_sel:[0,1]
	v_pk_mov_b32 v[6:7], v[0:1], v[0:1] op_sel:[0,1]
	v_pk_mov_b32 v[16:17], v[0:1], v[0:1] op_sel:[0,1]
	v_pk_mov_b32 v[18:19], v[0:1], v[0:1] op_sel:[0,1]
	v_pk_mov_b32 v[20:21], v[0:1], v[0:1] op_sel:[0,1]
	v_pk_mov_b32 v[22:23], v[0:1], v[0:1] op_sel:[0,1]
	v_pk_mov_b32 v[32:33], v[0:1], v[0:1] op_sel:[0,1]
	v_pk_mov_b32 v[34:35], v[0:1], v[0:1] op_sel:[0,1]
	v_pk_mov_b32 v[36:37], v[0:1], v[0:1] op_sel:[0,1]
	v_pk_mov_b32 v[38:39], v[0:1], v[0:1] op_sel:[0,1]
	v_pk_mov_b32 v[48:49], v[0:1], v[0:1] op_sel:[0,1]
	v_pk_mov_b32 v[50:51], v[0:1], v[0:1] op_sel:[0,1]
	v_pk_mov_b32 v[52:53], v[0:1], v[0:1] op_sel:[0,1]
	v_pk_mov_b32 v[54:55], v[0:1], v[0:1] op_sel:[0,1]
	v_pk_mov_b32 v[8:9], v[0:1], v[0:1] op_sel:[0,1]
	v_pk_mov_b32 v[10:11], v[0:1], v[0:1] op_sel:[0,1]
	v_pk_mov_b32 v[12:13], v[0:1], v[0:1] op_sel:[0,1]
	v_pk_mov_b32 v[14:15], v[0:1], v[0:1] op_sel:[0,1]
	v_pk_mov_b32 v[24:25], v[0:1], v[0:1] op_sel:[0,1]
	v_pk_mov_b32 v[26:27], v[0:1], v[0:1] op_sel:[0,1]
	v_pk_mov_b32 v[28:29], v[0:1], v[0:1] op_sel:[0,1]
	v_pk_mov_b32 v[30:31], v[0:1], v[0:1] op_sel:[0,1]
	v_pk_mov_b32 v[40:41], v[0:1], v[0:1] op_sel:[0,1]
	v_pk_mov_b32 v[42:43], v[0:1], v[0:1] op_sel:[0,1]
	v_pk_mov_b32 v[44:45], v[0:1], v[0:1] op_sel:[0,1]
	v_pk_mov_b32 v[46:47], v[0:1], v[0:1] op_sel:[0,1]
	v_pk_mov_b32 v[56:57], v[0:1], v[0:1] op_sel:[0,1]
	v_pk_mov_b32 v[58:59], v[0:1], v[0:1] op_sel:[0,1]
	v_pk_mov_b32 v[60:61], v[0:1], v[0:1] op_sel:[0,1]
	v_pk_mov_b32 v[62:63], v[0:1], v[0:1] op_sel:[0,1]
	v_pk_mov_b32 v[64:65], v[0:1], v[0:1] op_sel:[0,1]
	v_pk_mov_b32 v[66:67], v[0:1], v[0:1] op_sel:[0,1]
	v_pk_mov_b32 v[68:69], v[0:1], v[0:1] op_sel:[0,1]
	v_pk_mov_b32 v[70:71], v[0:1], v[0:1] op_sel:[0,1]
	v_pk_mov_b32 v[80:81], v[0:1], v[0:1] op_sel:[0,1]
	v_pk_mov_b32 v[82:83], v[0:1], v[0:1] op_sel:[0,1]
	v_pk_mov_b32 v[84:85], v[0:1], v[0:1] op_sel:[0,1]
	v_pk_mov_b32 v[86:87], v[0:1], v[0:1] op_sel:[0,1]
	v_pk_mov_b32 v[96:97], v[0:1], v[0:1] op_sel:[0,1]
	v_pk_mov_b32 v[98:99], v[0:1], v[0:1] op_sel:[0,1]
	v_pk_mov_b32 v[100:101], v[0:1], v[0:1] op_sel:[0,1]
	v_pk_mov_b32 v[102:103], v[0:1], v[0:1] op_sel:[0,1]
	v_pk_mov_b32 v[112:113], v[0:1], v[0:1] op_sel:[0,1]
	v_pk_mov_b32 v[114:115], v[0:1], v[0:1] op_sel:[0,1]
	v_pk_mov_b32 v[116:117], v[0:1], v[0:1] op_sel:[0,1]
	v_pk_mov_b32 v[118:119], v[0:1], v[0:1] op_sel:[0,1]
	v_pk_mov_b32 v[72:73], v[0:1], v[0:1] op_sel:[0,1]
	v_pk_mov_b32 v[74:75], v[0:1], v[0:1] op_sel:[0,1]
	v_pk_mov_b32 v[76:77], v[0:1], v[0:1] op_sel:[0,1]
	v_pk_mov_b32 v[78:79], v[0:1], v[0:1] op_sel:[0,1]
	v_pk_mov_b32 v[88:89], v[0:1], v[0:1] op_sel:[0,1]
	v_pk_mov_b32 v[90:91], v[0:1], v[0:1] op_sel:[0,1]
	v_pk_mov_b32 v[92:93], v[0:1], v[0:1] op_sel:[0,1]
	v_pk_mov_b32 v[94:95], v[0:1], v[0:1] op_sel:[0,1]
	v_pk_mov_b32 v[104:105], v[0:1], v[0:1] op_sel:[0,1]
	v_pk_mov_b32 v[106:107], v[0:1], v[0:1] op_sel:[0,1]
	v_pk_mov_b32 v[108:109], v[0:1], v[0:1] op_sel:[0,1]
	v_pk_mov_b32 v[110:111], v[0:1], v[0:1] op_sel:[0,1]
	v_pk_mov_b32 v[120:121], v[0:1], v[0:1] op_sel:[0,1]
	v_pk_mov_b32 v[122:123], v[0:1], v[0:1] op_sel:[0,1]
	v_pk_mov_b32 v[124:125], v[0:1], v[0:1] op_sel:[0,1]
	v_pk_mov_b32 v[126:127], v[0:1], v[0:1] op_sel:[0,1]

.LBB0_1859:
	s_add_i32 s73, s36, 2
	s_add_u32 s34, s30, 0x100
	s_addc_u32 s35, s31, 0
	s_add_i32 s74, 0, 0x10000
	s_cmp_eq_u32 s0, s36
	s_cselect_b32 s41, s25, s35
	s_cselect_b32 s40, s68, s34
	s_cselect_b32 s37, s23, s72
	s_cselect_b32 s36, s70, s71
	s_add_i32 s75, 0, 0x14000
	v_add_u32_e32 v152, s74, v138
	v_add_u32_e32 v168, s75, v138
	ds_read_b128 v[140:143], v152
	ds_read_b128 v[144:147], v152 offset:1024
	ds_read_b128 v[148:151], v152 offset:2048
	ds_read_b128 v[152:155], v152 offset:3072
	ds_read_b128 v[156:159], v168
	ds_read_b128 v[160:163], v168 offset:1024
	ds_read_b128 v[164:167], v168 offset:2048
	ds_read_b128 v[168:171], v168 offset:3072
	v_lshl_add_u64 v[204:205], s[30:31], 0, v[132:133]
	s_add_i32 m0, s56, 0xc000
	ds_read_b128 v[172:175], v139
	ds_read_b128 v[176:179], v139 offset:1024
	ds_read_b128 v[180:183], v139 offset:2048
	ds_read_b128 v[184:187], v139 offset:3072
	ds_read_b128 v[188:191], v139 offset:4096
	ds_read_b128 v[192:195], v139 offset:5120
	ds_read_b128 v[196:199], v139 offset:6144
	ds_read_b128 v[200:203], v139 offset:7168
	global_load_lds_dwordx4 v[204:205], off
	v_lshl_add_u64 v[204:205], s[30:31], 0, v[134:135]
	s_add_i32 m0, s56, 0xe000
	s_nop 0
	global_load_lds_dwordx4 v[204:205], off
	s_waitcnt vmcnt(8)
	s_waitcnt lgkmcnt(0)
	s_barrier
	s_setprio 1
	s_waitcnt lgkmcnt(0)
	v_mfma_f32_16x16x32_bf16 v[124:127], v[140:143], v[172:175], v[124:127]
	v_mfma_f32_16x16x32_bf16 v[108:111], v[148:151], v[172:175], v[108:111]
	v_mfma_f32_16x16x32_bf16 v[120:123], v[140:143], v[180:183], v[120:123]
	v_mfma_f32_16x16x32_bf16 v[104:107], v[148:151], v[180:183], v[104:107]
	v_mfma_f32_16x16x32_bf16 v[116:119], v[140:143], v[188:191], v[116:119]
	v_mfma_f32_16x16x32_bf16 v[100:103], v[148:151], v[188:191], v[100:103]
	v_mfma_f32_16x16x32_bf16 v[112:115], v[140:143], v[196:199], v[112:115]
	v_mfma_f32_16x16x32_bf16 v[96:99], v[148:151], v[196:199], v[96:99]
	v_mfma_f32_16x16x32_bf16 v[124:127], v[144:147], v[176:179], v[124:127]
	v_mfma_f32_16x16x32_bf16 v[108:111], v[152:155], v[176:179], v[108:111]
	v_mfma_f32_16x16x32_bf16 v[120:123], v[144:147], v[184:187], v[120:123]
	v_mfma_f32_16x16x32_bf16 v[104:107], v[152:155], v[184:187], v[104:107]
	v_mfma_f32_16x16x32_bf16 v[116:119], v[144:147], v[192:195], v[116:119]
	v_mfma_f32_16x16x32_bf16 v[100:103], v[152:155], v[192:195], v[100:103]
	v_mfma_f32_16x16x32_bf16 v[112:115], v[144:147], v[200:203], v[112:115]
	v_mfma_f32_16x16x32_bf16 v[96:99], v[152:155], v[200:203], v[96:99]
	s_setprio 0
	s_setprio 1
	v_mfma_f32_16x16x32_bf16 v[92:95], v[156:159], v[172:175], v[92:95]
	v_mfma_f32_16x16x32_bf16 v[76:79], v[164:167], v[172:175], v[76:79]
	v_mfma_f32_16x16x32_bf16 v[88:91], v[156:159], v[180:183], v[88:91]
	v_mfma_f32_16x16x32_bf16 v[72:75], v[164:167], v[180:183], v[72:75]
	v_mfma_f32_16x16x32_bf16 v[84:87], v[156:159], v[188:191], v[84:87]
	v_mfma_f32_16x16x32_bf16 v[68:71], v[164:167], v[188:191], v[68:71]
	v_mfma_f32_16x16x32_bf16 v[80:83], v[156:159], v[196:199], v[80:83]
	v_mfma_f32_16x16x32_bf16 v[64:67], v[164:167], v[196:199], v[64:67]
	v_mfma_f32_16x16x32_bf16 v[92:95], v[160:163], v[176:179], v[92:95]
	v_mfma_f32_16x16x32_bf16 v[76:79], v[168:171], v[176:179], v[76:79]
	v_mfma_f32_16x16x32_bf16 v[88:91], v[160:163], v[184:187], v[88:91]
	v_mfma_f32_16x16x32_bf16 v[72:75], v[168:171], v[184:187], v[72:75]
	v_mfma_f32_16x16x32_bf16 v[84:87], v[160:163], v[192:195], v[84:87]
	v_mfma_f32_16x16x32_bf16 v[68:71], v[168:171], v[192:195], v[68:71]
	v_mfma_f32_16x16x32_bf16 v[80:83], v[160:163], v[200:203], v[80:83]
	v_mfma_f32_16x16x32_bf16 v[64:67], v[168:171], v[200:203], v[64:67]
	s_setprio 0
	s_barrier
	s_add_i32 s30, s74, s54
	v_lshl_add_u64 v[204:205], s[36:37], 0, v[128:129]
	s_mov_b32 m0, s30
	ds_read_b128 v[172:175], v139 offset:16384
	ds_read_b128 v[176:179], v139 offset:17408
	ds_read_b128 v[180:183], v139 offset:18432
	ds_read_b128 v[184:187], v139 offset:19456
	ds_read_b128 v[188:191], v139 offset:20480
	ds_read_b128 v[192:195], v139 offset:21504
	ds_read_b128 v[196:199], v139 offset:22528
	ds_read_b128 v[200:203], v139 offset:23552
	global_load_lds_dwordx4 v[204:205], off
	s_add_i32 m0, s30, 0x2000
	s_add_u32 s30, s36, 0x100000
	v_lshl_add_u64 v[206:207], s[36:37], 0, v[130:131]
	s_addc_u32 s31, s37, 0
	s_add_i32 s74, s75, s54
	global_load_lds_dwordx4 v[206:207], off
	v_lshl_add_u64 v[208:209], s[30:31], 0, v[128:129]
	s_mov_b32 m0, s74
	v_lshl_add_u64 v[210:211], s[40:41], 0, v[130:131]
	global_load_lds_dwordx4 v[208:209], off
	v_lshl_add_u64 v[208:209], s[30:31], 0, v[130:131]
	s_add_i32 m0, s74, 0x2000
	s_nop 0
	global_load_lds_dwordx4 v[208:209], off
	v_lshl_add_u64 v[208:209], s[40:41], 0, v[128:129]
	s_mov_b32 m0, s56
	s_nop 0
	global_load_lds_dwordx4 v[208:209], off
	s_mov_b32 m0, s58
	s_nop 0
	global_load_lds_dwordx4 v[210:211], off
	s_waitcnt vmcnt(8)
	s_waitcnt lgkmcnt(0)
	s_barrier
	s_setprio 1
	s_waitcnt lgkmcnt(0)
	v_mfma_f32_16x16x32_bf16 v[60:63], v[140:143], v[172:175], v[60:63]
	v_mfma_f32_16x16x32_bf16 v[44:47], v[148:151], v[172:175], v[44:47]
	v_mfma_f32_16x16x32_bf16 v[56:59], v[140:143], v[180:183], v[56:59]
	v_mfma_f32_16x16x32_bf16 v[40:43], v[148:151], v[180:183], v[40:43]
	v_mfma_f32_16x16x32_bf16 v[52:55], v[140:143], v[188:191], v[52:55]
	v_mfma_f32_16x16x32_bf16 v[36:39], v[148:151], v[188:191], v[36:39]
	v_mfma_f32_16x16x32_bf16 v[48:51], v[140:143], v[196:199], v[48:51]
	v_mfma_f32_16x16x32_bf16 v[32:35], v[148:151], v[196:199], v[32:35]
	v_mfma_f32_16x16x32_bf16 v[60:63], v[144:147], v[176:179], v[60:63]
	v_mfma_f32_16x16x32_bf16 v[44:47], v[152:155], v[176:179], v[44:47]
	v_mfma_f32_16x16x32_bf16 v[56:59], v[144:147], v[184:187], v[56:59]
	v_mfma_f32_16x16x32_bf16 v[40:43], v[152:155], v[184:187], v[40:43]
	v_mfma_f32_16x16x32_bf16 v[52:55], v[144:147], v[192:195], v[52:55]
	v_mfma_f32_16x16x32_bf16 v[36:39], v[152:155], v[192:195], v[36:39]
	v_mfma_f32_16x16x32_bf16 v[48:51], v[144:147], v[200:203], v[48:51]
	v_mfma_f32_16x16x32_bf16 v[32:35], v[152:155], v[200:203], v[32:35]
	s_setprio 0
	s_setprio 1
	v_mfma_f32_16x16x32_bf16 v[28:31], v[156:159], v[172:175], v[28:31]
	v_mfma_f32_16x16x32_bf16 v[12:15], v[164:167], v[172:175], v[12:15]
	v_mfma_f32_16x16x32_bf16 v[24:27], v[156:159], v[180:183], v[24:27]
	v_mfma_f32_16x16x32_bf16 v[8:11], v[164:167], v[180:183], v[8:11]
	v_mfma_f32_16x16x32_bf16 v[20:23], v[156:159], v[188:191], v[20:23]
	v_mfma_f32_16x16x32_bf16 v[4:7], v[164:167], v[188:191], v[4:7]
	v_mfma_f32_16x16x32_bf16 v[16:19], v[156:159], v[196:199], v[16:19]
	v_mfma_f32_16x16x32_bf16 v[0:3], v[164:167], v[196:199], v[0:3]
	v_mfma_f32_16x16x32_bf16 v[28:31], v[160:163], v[176:179], v[28:31]
	v_mfma_f32_16x16x32_bf16 v[12:15], v[168:171], v[176:179], v[12:15]
	v_mfma_f32_16x16x32_bf16 v[24:27], v[160:163], v[184:187], v[24:27]
	v_mfma_f32_16x16x32_bf16 v[8:11], v[168:171], v[184:187], v[8:11]
	v_mfma_f32_16x16x32_bf16 v[20:23], v[160:163], v[192:195], v[20:23]
	v_mfma_f32_16x16x32_bf16 v[4:7], v[168:171], v[192:195], v[4:7]
	v_mfma_f32_16x16x32_bf16 v[16:19], v[160:163], v[200:203], v[16:19]
	v_mfma_f32_16x16x32_bf16 v[0:3], v[168:171], v[200:203], v[0:3]
	s_setprio 0
	s_barrier
	s_add_i32 s74, 0, 0x18000
	s_add_i32 s75, 0, 0x1c000
	v_add_u32_e32 v152, s74, v138
	v_add_u32_e32 v168, s75, v138
	ds_read_b128 v[140:143], v152
	ds_read_b128 v[144:147], v152 offset:1024
	ds_read_b128 v[148:151], v152 offset:2048
	ds_read_b128 v[152:155], v152 offset:3072
	ds_read_b128 v[156:159], v168
	ds_read_b128 v[160:163], v168 offset:1024
	ds_read_b128 v[164:167], v168 offset:2048
	ds_read_b128 v[168:171], v168 offset:3072
	s_add_u32 s30, s40, 0x100000
	s_addc_u32 s31, s41, 0
	s_mov_b32 m0, s59
	v_lshl_add_u64 v[212:213], s[30:31], 0, v[128:129]
	ds_read_b128 v[172:175], v139 offset:32768
	ds_read_b128 v[176:179], v139 offset:33792
	ds_read_b128 v[180:183], v139 offset:34816
	ds_read_b128 v[184:187], v139 offset:35840
	ds_read_b128 v[188:191], v139 offset:36864
	ds_read_b128 v[192:195], v139 offset:37888
	ds_read_b128 v[196:199], v139 offset:38912
	ds_read_b128 v[200:203], v139 offset:39936
	global_load_lds_dwordx4 v[212:213], off
	v_lshl_add_u64 v[212:213], s[30:31], 0, v[130:131]
	s_mov_b32 m0, s60
	s_nop 0
	global_load_lds_dwordx4 v[212:213], off
	s_waitcnt vmcnt(8)
	s_waitcnt lgkmcnt(0)
	s_barrier
	s_setprio 1
	s_waitcnt lgkmcnt(0)
	v_mfma_f32_16x16x32_bf16 v[124:127], v[140:143], v[172:175], v[124:127]
	v_mfma_f32_16x16x32_bf16 v[108:111], v[148:151], v[172:175], v[108:111]
	v_mfma_f32_16x16x32_bf16 v[120:123], v[140:143], v[180:183], v[120:123]
	v_mfma_f32_16x16x32_bf16 v[104:107], v[148:151], v[180:183], v[104:107]
	v_mfma_f32_16x16x32_bf16 v[116:119], v[140:143], v[188:191], v[116:119]
	v_mfma_f32_16x16x32_bf16 v[100:103], v[148:151], v[188:191], v[100:103]
	v_mfma_f32_16x16x32_bf16 v[112:115], v[140:143], v[196:199], v[112:115]
	v_mfma_f32_16x16x32_bf16 v[96:99], v[148:151], v[196:199], v[96:99]
	v_mfma_f32_16x16x32_bf16 v[124:127], v[144:147], v[176:179], v[124:127]
	v_mfma_f32_16x16x32_bf16 v[108:111], v[152:155], v[176:179], v[108:111]
	v_mfma_f32_16x16x32_bf16 v[120:123], v[144:147], v[184:187], v[120:123]
	v_mfma_f32_16x16x32_bf16 v[104:107], v[152:155], v[184:187], v[104:107]
	v_mfma_f32_16x16x32_bf16 v[116:119], v[144:147], v[192:195], v[116:119]
	v_mfma_f32_16x16x32_bf16 v[100:103], v[152:155], v[192:195], v[100:103]
	v_mfma_f32_16x16x32_bf16 v[112:115], v[144:147], v[200:203], v[112:115]
	v_mfma_f32_16x16x32_bf16 v[96:99], v[152:155], v[200:203], v[96:99]
	s_setprio 0
	s_setprio 1
	v_mfma_f32_16x16x32_bf16 v[92:95], v[156:159], v[172:175], v[92:95]
	v_mfma_f32_16x16x32_bf16 v[76:79], v[164:167], v[172:175], v[76:79]
	v_mfma_f32_16x16x32_bf16 v[88:91], v[156:159], v[180:183], v[88:91]
	v_mfma_f32_16x16x32_bf16 v[72:75], v[164:167], v[180:183], v[72:75]
	v_mfma_f32_16x16x32_bf16 v[84:87], v[156:159], v[188:191], v[84:87]
	v_mfma_f32_16x16x32_bf16 v[68:71], v[164:167], v[188:191], v[68:71]
	v_mfma_f32_16x16x32_bf16 v[80:83], v[156:159], v[196:199], v[80:83]
	v_mfma_f32_16x16x32_bf16 v[64:67], v[164:167], v[196:199], v[64:67]
	v_mfma_f32_16x16x32_bf16 v[92:95], v[160:163], v[176:179], v[92:95]
	v_mfma_f32_16x16x32_bf16 v[76:79], v[168:171], v[176:179], v[76:79]
	v_mfma_f32_16x16x32_bf16 v[88:91], v[160:163], v[184:187], v[88:91]
	v_mfma_f32_16x16x32_bf16 v[72:75], v[168:171], v[184:187], v[72:75]
	v_mfma_f32_16x16x32_bf16 v[84:87], v[160:163], v[192:195], v[84:87]
	v_mfma_f32_16x16x32_bf16 v[68:71], v[168:171], v[192:195], v[68:71]
	v_mfma_f32_16x16x32_bf16 v[80:83], v[160:163], v[200:203], v[80:83]
	v_mfma_f32_16x16x32_bf16 v[64:67], v[168:171], v[200:203], v[64:67]
	s_setprio 0
	s_barrier
	s_add_i32 s30, s74, s54
	v_lshl_add_u64 v[204:205], v[204:205], 0, s[6:7]
	s_mov_b32 m0, s30
	ds_read_b128 v[172:175], v139 offset:49152
	ds_read_b128 v[176:179], v139 offset:50176
	ds_read_b128 v[180:183], v139 offset:51200
	ds_read_b128 v[184:187], v139 offset:52224
	ds_read_b128 v[188:191], v139 offset:53248
	ds_read_b128 v[192:195], v139 offset:54272
	ds_read_b128 v[196:199], v139 offset:55296
	ds_read_b128 v[200:203], v139 offset:56320
	global_load_lds_dwordx4 v[204:205], off
	s_add_i32 m0, s30, 0x2000
	s_add_u32 s30, s36, 0x100080
	v_lshl_add_u64 v[204:205], v[206:207], 0, s[6:7]
	s_addc_u32 s31, s37, 0
	s_add_i32 s36, s75, s54
	global_load_lds_dwordx4 v[204:205], off
	v_lshl_add_u64 v[204:205], s[30:31], 0, v[128:129]
	s_mov_b32 m0, s36
	s_nop 0
	global_load_lds_dwordx4 v[204:205], off
	v_lshl_add_u64 v[204:205], s[30:31], 0, v[130:131]
	s_add_i32 m0, s36, 0x2000
	s_nop 0
	global_load_lds_dwordx4 v[204:205], off
	v_lshl_add_u64 v[204:205], v[208:209], 0, s[6:7]
	s_mov_b32 m0, s61
	s_nop 0
	global_load_lds_dwordx4 v[204:205], off
	v_lshl_add_u64 v[204:205], v[210:211], 0, s[6:7]
	s_mov_b32 m0, s62
	s_nop 0
	global_load_lds_dwordx4 v[204:205], off
	s_waitcnt vmcnt(8)
	s_waitcnt lgkmcnt(0)
	s_barrier
	s_setprio 1
	s_waitcnt lgkmcnt(0)
	v_mfma_f32_16x16x32_bf16 v[60:63], v[140:143], v[172:175], v[60:63]
	v_mfma_f32_16x16x32_bf16 v[44:47], v[148:151], v[172:175], v[44:47]
	v_mfma_f32_16x16x32_bf16 v[56:59], v[140:143], v[180:183], v[56:59]
	v_mfma_f32_16x16x32_bf16 v[40:43], v[148:151], v[180:183], v[40:43]
	v_mfma_f32_16x16x32_bf16 v[52:55], v[140:143], v[188:191], v[52:55]
	v_mfma_f32_16x16x32_bf16 v[36:39], v[148:151], v[188:191], v[36:39]
	v_mfma_f32_16x16x32_bf16 v[48:51], v[140:143], v[196:199], v[48:51]
	v_mfma_f32_16x16x32_bf16 v[32:35], v[148:151], v[196:199], v[32:35]
	v_mfma_f32_16x16x32_bf16 v[60:63], v[144:147], v[176:179], v[60:63]
	v_mfma_f32_16x16x32_bf16 v[44:47], v[152:155], v[176:179], v[44:47]
	v_mfma_f32_16x16x32_bf16 v[56:59], v[144:147], v[184:187], v[56:59]
	v_mfma_f32_16x16x32_bf16 v[40:43], v[152:155], v[184:187], v[40:43]
	v_mfma_f32_16x16x32_bf16 v[52:55], v[144:147], v[192:195], v[52:55]
	v_mfma_f32_16x16x32_bf16 v[36:39], v[152:155], v[192:195], v[36:39]
	v_mfma_f32_16x16x32_bf16 v[48:51], v[144:147], v[200:203], v[48:51]
	v_mfma_f32_16x16x32_bf16 v[32:35], v[152:155], v[200:203], v[32:35]
	s_setprio 0
	s_setprio 1
	v_mfma_f32_16x16x32_bf16 v[28:31], v[156:159], v[172:175], v[28:31]
	v_mfma_f32_16x16x32_bf16 v[12:15], v[164:167], v[172:175], v[12:15]
	v_mfma_f32_16x16x32_bf16 v[24:27], v[156:159], v[180:183], v[24:27]
	v_mfma_f32_16x16x32_bf16 v[8:11], v[164:167], v[180:183], v[8:11]
	v_mfma_f32_16x16x32_bf16 v[20:23], v[156:159], v[188:191], v[20:23]
	v_mfma_f32_16x16x32_bf16 v[4:7], v[164:167], v[188:191], v[4:7]
	v_mfma_f32_16x16x32_bf16 v[16:19], v[156:159], v[196:199], v[16:19]
	v_mfma_f32_16x16x32_bf16 v[0:3], v[164:167], v[196:199], v[0:3]
	v_mfma_f32_16x16x32_bf16 v[28:31], v[160:163], v[176:179], v[28:31]
	v_mfma_f32_16x16x32_bf16 v[12:15], v[168:171], v[176:179], v[12:15]
	v_mfma_f32_16x16x32_bf16 v[24:27], v[160:163], v[184:187], v[24:27]
	v_mfma_f32_16x16x32_bf16 v[8:11], v[168:171], v[184:187], v[8:11]
	v_mfma_f32_16x16x32_bf16 v[20:23], v[160:163], v[192:195], v[20:23]
	v_mfma_f32_16x16x32_bf16 v[4:7], v[168:171], v[192:195], v[4:7]
	v_mfma_f32_16x16x32_bf16 v[16:19], v[160:163], v[200:203], v[16:19]
	v_mfma_f32_16x16x32_bf16 v[0:3], v[168:171], v[200:203], v[0:3]
	s_setprio 0
	s_barrier
	s_add_u32 s71, s71, 0x100
	s_addc_u32 s72, s72, 0
	s_cmp_ge_u32 s73, s67
	s_mov_b64 s[30:31], s[34:35]
	s_mov_b32 s36, s73
	s_cbranch_scc0 .LBB0_1859
	s_andn2_b64 vcc, exec, s[48:49]
	s_cbranch_vccnz .LBB0_1851
	v_mov_b32_e32 v0, 0
	s_mov_b32 s64, s22
	s_mov_b32 s63, s24
	s_mov_b64 s[18:19], s[28:29]
	s_mov_b64 s[20:21], s[26:27]
	s_mov_b32 s65, s66
	v_mov_b32_e32 v1, v0
	v_pk_mov_b32 v[2:3], v[0:1], v[0:1] op_sel:[0,1]
	v_pk_mov_b32 v[16:17], v[0:1], v[0:1] op_sel:[0,1]
	v_pk_mov_b32 v[18:19], v[0:1], v[0:1] op_sel:[0,1]
	v_pk_mov_b32 v[4:5], v[0:1], v[0:1] op_sel:[0,1]
	v_pk_mov_b32 v[6:7], v[0:1], v[0:1] op_sel:[0,1]
	v_pk_mov_b32 v[20:21], v[0:1], v[0:1] op_sel:[0,1]
	v_pk_mov_b32 v[22:23], v[0:1], v[0:1] op_sel:[0,1]
	v_pk_mov_b32 v[8:9], v[0:1], v[0:1] op_sel:[0,1]
	v_pk_mov_b32 v[10:11], v[0:1], v[0:1] op_sel:[0,1]
	v_pk_mov_b32 v[24:25], v[0:1], v[0:1] op_sel:[0,1]
	v_pk_mov_b32 v[26:27], v[0:1], v[0:1] op_sel:[0,1]
	v_pk_mov_b32 v[12:13], v[0:1], v[0:1] op_sel:[0,1]
	v_pk_mov_b32 v[14:15], v[0:1], v[0:1] op_sel:[0,1]
	v_pk_mov_b32 v[28:29], v[0:1], v[0:1] op_sel:[0,1]
	v_pk_mov_b32 v[30:31], v[0:1], v[0:1] op_sel:[0,1]
	v_pk_mov_b32 v[32:33], v[0:1], v[0:1] op_sel:[0,1]
	v_pk_mov_b32 v[34:35], v[0:1], v[0:1] op_sel:[0,1]
	v_pk_mov_b32 v[48:49], v[0:1], v[0:1] op_sel:[0,1]
	v_pk_mov_b32 v[50:51], v[0:1], v[0:1] op_sel:[0,1]
	v_pk_mov_b32 v[36:37], v[0:1], v[0:1] op_sel:[0,1]
	v_pk_mov_b32 v[38:39], v[0:1], v[0:1] op_sel:[0,1]
	v_pk_mov_b32 v[52:53], v[0:1], v[0:1] op_sel:[0,1]
	v_pk_mov_b32 v[54:55], v[0:1], v[0:1] op_sel:[0,1]
	v_pk_mov_b32 v[40:41], v[0:1], v[0:1] op_sel:[0,1]
	v_pk_mov_b32 v[42:43], v[0:1], v[0:1] op_sel:[0,1]
	v_pk_mov_b32 v[56:57], v[0:1], v[0:1] op_sel:[0,1]
	v_pk_mov_b32 v[58:59], v[0:1], v[0:1] op_sel:[0,1]
	v_pk_mov_b32 v[44:45], v[0:1], v[0:1] op_sel:[0,1]
	v_pk_mov_b32 v[46:47], v[0:1], v[0:1] op_sel:[0,1]
	v_pk_mov_b32 v[60:61], v[0:1], v[0:1] op_sel:[0,1]
	v_pk_mov_b32 v[62:63], v[0:1], v[0:1] op_sel:[0,1]
	v_pk_mov_b32 v[64:65], v[0:1], v[0:1] op_sel:[0,1]
	v_pk_mov_b32 v[66:67], v[0:1], v[0:1] op_sel:[0,1]
	v_pk_mov_b32 v[80:81], v[0:1], v[0:1] op_sel:[0,1]
	v_pk_mov_b32 v[82:83], v[0:1], v[0:1] op_sel:[0,1]
	v_pk_mov_b32 v[68:69], v[0:1], v[0:1] op_sel:[0,1]
	v_pk_mov_b32 v[70:71], v[0:1], v[0:1] op_sel:[0,1]
	v_pk_mov_b32 v[84:85], v[0:1], v[0:1] op_sel:[0,1]
	v_pk_mov_b32 v[86:87], v[0:1], v[0:1] op_sel:[0,1]
	v_pk_mov_b32 v[72:73], v[0:1], v[0:1] op_sel:[0,1]
	v_pk_mov_b32 v[74:75], v[0:1], v[0:1] op_sel:[0,1]
	v_pk_mov_b32 v[88:89], v[0:1], v[0:1] op_sel:[0,1]
	v_pk_mov_b32 v[90:91], v[0:1], v[0:1] op_sel:[0,1]
	v_pk_mov_b32 v[76:77], v[0:1], v[0:1] op_sel:[0,1]
	v_pk_mov_b32 v[78:79], v[0:1], v[0:1] op_sel:[0,1]
	v_pk_mov_b32 v[92:93], v[0:1], v[0:1] op_sel:[0,1]
	v_pk_mov_b32 v[94:95], v[0:1], v[0:1] op_sel:[0,1]
	v_pk_mov_b32 v[96:97], v[0:1], v[0:1] op_sel:[0,1]
	v_pk_mov_b32 v[98:99], v[0:1], v[0:1] op_sel:[0,1]
	v_pk_mov_b32 v[112:113], v[0:1], v[0:1] op_sel:[0,1]
	v_pk_mov_b32 v[114:115], v[0:1], v[0:1] op_sel:[0,1]
	v_pk_mov_b32 v[100:101], v[0:1], v[0:1] op_sel:[0,1]
	v_pk_mov_b32 v[102:103], v[0:1], v[0:1] op_sel:[0,1]
	v_pk_mov_b32 v[116:117], v[0:1], v[0:1] op_sel:[0,1]
	v_pk_mov_b32 v[118:119], v[0:1], v[0:1] op_sel:[0,1]
	v_pk_mov_b32 v[104:105], v[0:1], v[0:1] op_sel:[0,1]
	v_pk_mov_b32 v[106:107], v[0:1], v[0:1] op_sel:[0,1]
	v_pk_mov_b32 v[120:121], v[0:1], v[0:1] op_sel:[0,1]
	v_pk_mov_b32 v[122:123], v[0:1], v[0:1] op_sel:[0,1]
	v_pk_mov_b32 v[108:109], v[0:1], v[0:1] op_sel:[0,1]
	v_pk_mov_b32 v[110:111], v[0:1], v[0:1] op_sel:[0,1]
	v_pk_mov_b32 v[124:125], v[0:1], v[0:1] op_sel:[0,1]
	v_pk_mov_b32 v[126:127], v[0:1], v[0:1] op_sel:[0,1]
	s_branch .LBB0_1851
